# gate/up epilogue: per-row-group private temporaries so the eight rstd chains and the exp stream overlap under the list scheduler (first exp issues ~25 slots earlier)
# baseline (speedup 1.0000x reference)
; __device__ __forceinline__ unsigned pk2(float lo, float hi) { unsigned r; asm("v_cvt_pk_bf16_f32 %0, %1, %2" : "=v"(r) : "v"(lo), "v"(hi)); return r; }
; __device__ __forceinline__ float sigmoidf_(float v) { return __builtin_amdgcn_rcpf(1.0f + fexp(-v)); }
; __device__ __forceinline__ void row_rstd8(const ssq_t* ss, int row0, float (&r)[8]) {
;     ssq_t sv[8];
; #pragma unroll
;     for (int k = 0; k < 8; ++k) sv[k] = ss[row0 + (k >> 2) * 128 + (k & 3) * 16];
;     asm volatile("" ::: "memory");
; #pragma unroll
;     for (int k = 0; k < 8; ++k) r[k] = rsqrtf((float)sv[k] * (1.0f / SSQ_SCALE) * (1.0f / D) + EPS);
; }
;     __device__ __forceinline__ bool operator()(f32x4 (&acc)[2][2][4][2], const pg8::Unit& u, int wr, int wc, int fr, int fq) const {
;         const int row0 = u.pm * 256 + wr * 64 + fr, col0 = u.pn * 128 + wc * 32 + 8 * fq;
;         float rr[8]; row_rstd8(ss, row0, rr);
; #pragma unroll
;         for (int ai = 0; ai < 2; ++ai)
; #pragma unroll
;             for (int m = 0; m < 4; ++m) {
;                 const int row = row0 + ai * 128 + m * 16; const float r = rr[ai * 4 + m];
;                 float o[8];
; #pragma unroll
;                 for (int n = 0; n < 2; ++n)
; #pragma unroll
;                     for (int j = 0; j < 4; ++j) { const float gv = acc[ai][0][m][n][j] * r, uv = acc[ai][1][m][n][j] * r; o[n * 4 + j] = gv * sigmoidf_(gv) * uv; }
;                 u32x4 w; w.x = pk2(o[0], o[1]); w.y = pk2(o[2], o[3]); w.z = pk2(o[4], o[5]); w.w = pk2(o[6], o[7]);
;                 *(u32x4*)(act + (size_t)row * FF + col0) = w;
.LBB0_97:
	v_lshl_add_u32 v140, s35, 8, v151
	v_readlane_b32 s6, v255, 31
	v_ashrrev_i32_e32 v141, 31, v140
	v_readlane_b32 s7, v255, 32
	v_lshl_or_b32 v156, s34, 7, v155
	v_ashrrev_i32_e32 v157, 31, v156
	v_lshl_add_u64 v[142:143], v[140:141], 3, s[6:7]
	global_load_dwordx2 v[160:161], v[142:143], off
	global_load_dwordx2 v[162:163], v[142:143], off offset:128
	global_load_dwordx2 v[164:165], v[142:143], off offset:256
	global_load_dwordx2 v[166:167], v[142:143], off offset:384
	global_load_dwordx2 v[146:147], v[142:143], off offset:1024
	global_load_dwordx2 v[148:149], v[142:143], off offset:1152
	global_load_dwordx2 v[144:145], v[142:143], off offset:1280
	s_nop 0
	global_load_dwordx2 v[142:143], v[142:143], off offset:1408
	v_lshlrev_b64 v[156:157], 1, v[156:157]
	v_lshl_add_u64 v[156:157], v[156:157], 0, s[90:91]
	v_mad_i64_i32 v[156:157], s[6:7], v140, s37, v[156:157]
	v_mov_b32_e32 v140, 1.0
	v_mov_b32_e32 v141, 1.0
	v_pk_mul_f32 v[122:123], v[122:123], v[126:127]
	v_pk_mul_f32 v[124:125], v[124:125], v[128:129]
	v_pk_mul_f32 v[114:115], v[114:115], v[118:119]
	v_pk_mul_f32 v[116:117], v[116:117], v[120:121]
	v_pk_mul_f32 v[106:107], v[106:107], v[110:111]
	v_pk_mul_f32 v[108:109], v[108:109], v[112:113]
	v_pk_mul_f32 v[98:99], v[98:99], v[102:103]
	v_pk_mul_f32 v[100:101], v[100:101], v[104:105]
	v_pk_mul_f32 v[90:91], v[90:91], v[94:95]
	v_pk_mul_f32 v[92:93], v[92:93], v[96:97]
	v_pk_mul_f32 v[82:83], v[82:83], v[86:87]
	v_pk_mul_f32 v[84:85], v[84:85], v[88:89]
	v_pk_mul_f32 v[74:75], v[74:75], v[78:79]
	v_pk_mul_f32 v[76:77], v[76:77], v[80:81]
	v_pk_mul_f32 v[66:67], v[66:67], v[70:71]
	v_pk_mul_f32 v[68:69], v[68:69], v[72:73]
	v_pk_mul_f32 v[58:59], v[58:59], v[62:63]
	v_pk_mul_f32 v[60:61], v[60:61], v[64:65]
	v_pk_mul_f32 v[50:51], v[50:51], v[54:55]
	v_pk_mul_f32 v[52:53], v[52:53], v[56:57]
	v_pk_mul_f32 v[42:43], v[42:43], v[46:47]
	v_pk_mul_f32 v[44:45], v[44:45], v[48:49]
	v_pk_mul_f32 v[34:35], v[34:35], v[38:39]
	v_pk_mul_f32 v[36:37], v[36:37], v[40:41]
	v_pk_mul_f32 v[26:27], v[26:27], v[30:31]
	v_pk_mul_f32 v[28:29], v[28:29], v[32:33]
	v_pk_mul_f32 v[18:19], v[18:19], v[22:23]
	v_pk_mul_f32 v[20:21], v[20:21], v[24:25]
	v_pk_mul_f32 v[10:11], v[10:11], v[14:15]
	v_pk_mul_f32 v[12:13], v[12:13], v[16:17]
	v_pk_mul_f32 v[2:3], v[2:3], v[6:7]
	v_pk_mul_f32 v[4:5], v[4:5], v[8:9]
	s_mov_b32 s6, 0x2c000
	s_mov_b32 s7, 0
	s_waitcnt vmcnt(0)
	v_ffbh_u32_e32 v168, v161
	v_min_u32_e32 v168, 32, v168
	v_lshlrev_b64 v[160:161], v168, v[160:161]
	v_ffbh_u32_e32 v170, v163
	v_min_u32_e32 v198, 1, v160
	v_min_u32_e32 v170, 32, v170
	v_or_b32_e32 v198, v161, v198
	v_lshlrev_b64 v[162:163], v170, v[162:163]
	v_ffbh_u32_e32 v172, v165
	v_cvt_f32_u32_e32 v198, v198
	v_sub_u32_e32 v168, 32, v168
	v_min_u32_e32 v200, 1, v162
	v_min_u32_e32 v172, 32, v172
	v_ldexp_f32 v198, v198, v168
	v_or_b32_e32 v200, v163, v200
	v_lshlrev_b64 v[164:165], v172, v[164:165]
	v_ffbh_u32_e32 v174, v167
	v_mul_f32_e32 v198, 0x33800000, v198
	v_cvt_f32_u32_e32 v200, v200
	v_sub_u32_e32 v170, 32, v170
	v_min_u32_e32 v202, 1, v164
	v_min_u32_e32 v174, 32, v174
	v_fmamk_f32 v198, v198, 0x3a000000, v218
	v_rsq_f32_e32 v160, v198
	v_ldexp_f32 v200, v200, v170
	v_or_b32_e32 v202, v165, v202
	v_lshlrev_b64 v[166:167], v174, v[166:167]
	v_ffbh_u32_e32 v176, v147
	v_mul_f32_e32 v200, 0x33800000, v200
	v_cvt_f32_u32_e32 v202, v202
	v_sub_u32_e32 v172, 32, v172
	v_min_u32_e32 v204, 1, v166
	v_min_u32_e32 v176, 32, v176
	v_fmamk_f32 v200, v200, 0x3a000000, v218
	v_rsq_f32_e32 v162, v200
	v_ldexp_f32 v202, v202, v172
	v_or_b32_e32 v204, v167, v204
	v_lshlrev_b64 v[146:147], v176, v[146:147]
	v_ffbh_u32_e32 v178, v149
	v_mul_f32_e32 v202, 0x33800000, v202
	v_cvt_f32_u32_e32 v204, v204
	v_sub_u32_e32 v174, 32, v174
	v_min_u32_e32 v206, 1, v146
	v_min_u32_e32 v178, 32, v178
	v_fmamk_f32 v202, v202, 0x3a000000, v218
	v_rsq_f32_e32 v164, v202
	v_ldexp_f32 v204, v204, v174
	v_or_b32_e32 v206, v147, v206
	v_lshlrev_b64 v[148:149], v178, v[148:149]
	v_ffbh_u32_e32 v194, v145
	v_mul_f32_e32 v204, 0x33800000, v204
	v_cvt_f32_u32_e32 v206, v206
	v_sub_u32_e32 v176, 32, v176
	v_min_u32_e32 v208, 1, v148
	v_min_u32_e32 v194, 32, v194
	v_mul_f32_e32 v168, 0xbfb8aa3b, v160
	v_fmamk_f32 v204, v204, 0x3a000000, v218
	v_rsq_f32_e32 v166, v204
	v_ldexp_f32 v206, v206, v176
	v_or_b32_e32 v208, v149, v208
	v_lshlrev_b64 v[144:145], v194, v[144:145]
	v_ffbh_u32_e32 v196, v143
	v_pk_mul_f32 v[126:127], v[126:127], v[168:169] op_sel_hi:[1,0]
	v_pk_mul_f32 v[128:129], v[128:129], v[168:169] op_sel_hi:[1,0]
	v_exp_f32_e32 v126, v126
	v_pk_mul_f32 v[118:119], v[118:119], v[168:169] op_sel_hi:[1,0]
	v_pk_mul_f32 v[120:121], v[120:121], v[168:169] op_sel_hi:[1,0]
	v_exp_f32_e32 v127, v127
	v_mul_f32_e32 v206, 0x33800000, v206
	v_cvt_f32_u32_e32 v208, v208
	v_exp_f32_e32 v128, v128
	v_sub_u32_e32 v178, 32, v178
	v_min_u32_e32 v210, 1, v144
	v_exp_f32_e32 v129, v129
	v_min_u32_e32 v196, 32, v196
	v_mul_f32_e32 v170, 0xbfb8aa3b, v162
	v_exp_f32_e32 v118, v118
	v_fmamk_f32 v206, v206, 0x3a000000, v218
	v_ldexp_f32 v208, v208, v178
	v_exp_f32_e32 v119, v119
	v_or_b32_e32 v210, v145, v210
	v_lshlrev_b64 v[142:143], v196, v[142:143]
	v_exp_f32_e32 v120, v120
	v_pk_mul_f32 v[110:111], v[110:111], v[170:171] op_sel_hi:[1,0]
	v_pk_mul_f32 v[112:113], v[112:113], v[170:171] op_sel_hi:[1,0]
	v_exp_f32_e32 v121, v121
	v_pk_mul_f32 v[102:103], v[102:103], v[170:171] op_sel_hi:[1,0]
	v_pk_mul_f32 v[104:105], v[104:105], v[170:171] op_sel_hi:[1,0]
	v_rsq_f32_e32 v146, v206
	v_mul_f32_e32 v208, 0x33800000, v208
	v_cvt_f32_u32_e32 v210, v210
	v_exp_f32_e32 v110, v110
	v_sub_u32_e32 v194, 32, v194
; __device__ __forceinline__ unsigned pk2(float lo, float hi) { unsigned r; asm("v_cvt_pk_bf16_f32 %0, %1, %2" : "=v"(r) : "v"(lo), "v"(hi)); return r; }
; __device__ __forceinline__ float sigmoidf_(float v) { return __builtin_amdgcn_rcpf(1.0f + fexp(-v)); }
;     __device__ __forceinline__ bool operator()(f32x4 (&acc)[2][2][4][2], const pg8::Unit& u, int wr, int wc, int fr, int fq) const {
;     ...
;                 const int row = row0 + ai * 128 + m * 16; const float r = rr[ai * 4 + m];
;                 float o[8];
; #pragma unroll
;                 for (int n = 0; n < 2; ++n)
; #pragma unroll
;                     for (int j = 0; j < 4; ++j) { const float gv = acc[ai][0][m][n][j] * r, uv = acc[ai][1][m][n][j] * r; o[n * 4 + j] = gv * sigmoidf_(gv) * uv; }
;                 u32x4 w; w.x = pk2(o[0], o[1]); w.y = pk2(o[2], o[3]); w.z = pk2(o[4], o[5]); w.w = pk2(o[6], o[7]);
;                 *(u32x4*)(act + (size_t)row * FF + col0) = w;
	v_min_u32_e32 v212, 1, v142
	v_exp_f32_e32 v111, v111
	v_mul_f32_e32 v172, 0xbfb8aa3b, v164
	v_fmamk_f32 v208, v208, 0x3a000000, v218
	v_exp_f32_e32 v112, v112
	v_ldexp_f32 v210, v210, v194
	v_or_b32_e32 v212, v143, v212
	v_exp_f32_e32 v113, v113
	v_pk_mul_f32 v[94:95], v[94:95], v[172:173] op_sel_hi:[1,0]
	v_pk_mul_f32 v[96:97], v[96:97], v[172:173] op_sel_hi:[1,0]
	v_exp_f32_e32 v102, v102
	v_pk_mul_f32 v[86:87], v[86:87], v[172:173] op_sel_hi:[1,0]
	v_pk_mul_f32 v[88:89], v[88:89], v[172:173] op_sel_hi:[1,0]
	v_exp_f32_e32 v103, v103
	v_mul_f32_e32 v210, 0x33800000, v210
	v_cvt_f32_u32_e32 v212, v212
	v_exp_f32_e32 v104, v104
	v_sub_u32_e32 v196, 32, v196
	v_pk_add_f32 v[126:127], v[126:127], v[140:141]
	v_exp_f32_e32 v105, v105
	v_pk_add_f32 v[128:129], v[128:129], v[140:141]
	v_pk_add_f32 v[118:119], v[118:119], v[140:141]
	v_rsq_f32_e32 v148, v208
	v_pk_add_f32 v[120:121], v[120:121], v[140:141]
	v_mul_f32_e32 v174, 0xbfb8aa3b, v166
	v_exp_f32_e32 v94, v94
	v_fmamk_f32 v210, v210, 0x3a000000, v218
	v_ldexp_f32 v212, v212, v196
	v_exp_f32_e32 v95, v95
	v_pk_mul_f32 v[78:79], v[78:79], v[174:175] op_sel_hi:[1,0]
	v_pk_mul_f32 v[80:81], v[80:81], v[174:175] op_sel_hi:[1,0]
	v_exp_f32_e32 v96, v96
	v_pk_mul_f32 v[70:71], v[70:71], v[174:175] op_sel_hi:[1,0]
	v_pk_mul_f32 v[72:73], v[72:73], v[174:175] op_sel_hi:[1,0]
	v_exp_f32_e32 v97, v97
	v_mul_f32_e32 v212, 0x33800000, v212
	v_pk_add_f32 v[110:111], v[110:111], v[140:141]
	v_exp_f32_e32 v86, v86
	v_pk_add_f32 v[112:113], v[112:113], v[140:141]
	v_pk_add_f32 v[102:103], v[102:103], v[140:141]
	v_exp_f32_e32 v87, v87
	v_pk_add_f32 v[104:105], v[104:105], v[140:141]
	v_mul_f32_e32 v176, 0xbfb8aa3b, v146
	v_exp_f32_e32 v88, v88
	v_fmamk_f32 v212, v212, 0x3a000000, v218
	v_mul_f32_e32 v198, v160, v160
	v_exp_f32_e32 v89, v89
	v_pk_mul_f32 v[62:63], v[62:63], v[176:177] op_sel_hi:[1,0]
	v_pk_mul_f32 v[64:65], v[64:65], v[176:177] op_sel_hi:[1,0]
	v_rcp_f32_e32 v126, v126
	v_pk_mul_f32 v[54:55], v[54:55], v[176:177] op_sel_hi:[1,0]
	v_pk_mul_f32 v[56:57], v[56:57], v[176:177] op_sel_hi:[1,0]
	v_rcp_f32_e32 v127, v127
	v_pk_mul_f32 v[122:123], v[122:123], v[198:199] op_sel_hi:[1,0]
	v_pk_mul_f32 v[124:125], v[124:125], v[198:199] op_sel_hi:[1,0]
	v_rcp_f32_e32 v128, v128
	v_pk_mul_f32 v[114:115], v[114:115], v[198:199] op_sel_hi:[1,0]
	v_pk_mul_f32 v[116:117], v[116:117], v[198:199] op_sel_hi:[1,0]
	v_rcp_f32_e32 v129, v129
	v_pk_add_f32 v[94:95], v[94:95], v[140:141]
	v_pk_add_f32 v[96:97], v[96:97], v[140:141]
	v_rcp_f32_e32 v118, v118
	v_pk_add_f32 v[86:87], v[86:87], v[140:141]
	v_pk_add_f32 v[88:89], v[88:89], v[140:141]
	v_rcp_f32_e32 v119, v119
	v_mul_f32_e32 v178, 0xbfb8aa3b, v148
	v_pk_mul_f32 v[122:123], v[122:123], v[126:127]
	v_rcp_f32_e32 v120, v120
	v_pk_mul_f32 v[124:125], v[124:125], v[128:129]
	v_pk_mul_f32 v[114:115], v[114:115], v[118:119]
	v_rcp_f32_e32 v121, v121
	v_mul_f32_e32 v200, v162, v162
	v_pk_mul_f32 v[116:117], v[116:117], v[120:121]
	v_rsq_f32_e32 v144, v210
	v_pk_mul_f32 v[46:47], v[46:47], v[178:179] op_sel_hi:[1,0]
	v_pk_mul_f32 v[48:49], v[48:49], v[178:179] op_sel_hi:[1,0]
	v_exp_f32_e32 v78, v78
	v_pk_mul_f32 v[38:39], v[38:39], v[178:179] op_sel_hi:[1,0]
	v_pk_mul_f32 v[40:41], v[40:41], v[178:179] op_sel_hi:[1,0]
	v_exp_f32_e32 v79, v79
	v_cvt_pk_bf16_f32 v126, v122, v123
	v_cvt_pk_bf16_f32 v127, v124, v125
	v_exp_f32_e32 v80, v80
	v_cvt_pk_bf16_f32 v128, v114, v115
	v_cvt_pk_bf16_f32 v129, v116, v117
	v_exp_f32_e32 v81, v81
	v_pk_mul_f32 v[106:107], v[106:107], v[200:201] op_sel_hi:[1,0]
	v_pk_mul_f32 v[108:109], v[108:109], v[200:201] op_sel_hi:[1,0]
	v_exp_f32_e32 v70, v70
	v_pk_mul_f32 v[98:99], v[98:99], v[200:201] op_sel_hi:[1,0]
	v_pk_mul_f32 v[100:101], v[100:101], v[200:201] op_sel_hi:[1,0]
	v_exp_f32_e32 v71, v71
	v_pk_add_f32 v[78:79], v[78:79], v[140:141]
	v_pk_add_f32 v[80:81], v[80:81], v[140:141]
	v_exp_f32_e32 v72, v72
	v_pk_add_f32 v[70:71], v[70:71], v[140:141]
	v_mul_f32_e32 v194, 0xbfb8aa3b, v144
	v_exp_f32_e32 v73, v73
	global_store_dwordx4 v[156:157], v[126:129], off
	v_pk_add_f32 v[72:73], v[72:73], v[140:141]
	v_rcp_f32_e32 v110, v110
	v_mul_f32_e32 v202, v164, v164
	v_pk_mul_f32 v[30:31], v[30:31], v[194:195] op_sel_hi:[1,0]
	v_rcp_f32_e32 v111, v111
	v_pk_mul_f32 v[32:33], v[32:33], v[194:195] op_sel_hi:[1,0]
	v_pk_mul_f32 v[106:107], v[106:107], v[110:111]
	v_rcp_f32_e32 v112, v112
	v_pk_mul_f32 v[22:23], v[22:23], v[194:195] op_sel_hi:[1,0]
	v_pk_mul_f32 v[24:25], v[24:25], v[194:195] op_sel_hi:[1,0]
	v_rcp_f32_e32 v113, v113
	v_lshl_add_u64 v[156:157], v[156:157], 0, s[6:7]
	v_pk_mul_f32 v[108:109], v[108:109], v[112:113]
	v_rcp_f32_e32 v102, v102
	v_cvt_pk_bf16_f32 v110, v106, v107
	v_cvt_pk_bf16_f32 v111, v108, v109
	v_rcp_f32_e32 v103, v103
	v_pk_mul_f32 v[90:91], v[90:91], v[202:203] op_sel_hi:[1,0]
	v_pk_mul_f32 v[98:99], v[98:99], v[102:103]
	v_rcp_f32_e32 v104, v104
	v_cvt_pk_bf16_f32 v112, v98, v99
	v_pk_mul_f32 v[92:93], v[92:93], v[202:203] op_sel_hi:[1,0]
	v_rcp_f32_e32 v105, v105
	v_pk_mul_f32 v[82:83], v[82:83], v[202:203] op_sel_hi:[1,0]
	v_pk_mul_f32 v[100:101], v[100:101], v[104:105]
	v_rsq_f32_e32 v142, v212
	v_cvt_pk_bf16_f32 v113, v100, v101
	v_pk_mul_f32 v[84:85], v[84:85], v[202:203] op_sel_hi:[1,0]
	v_exp_f32_e32 v62, v62
	v_mul_f32_e32 v196, 0xbfb8aa3b, v142
	global_store_dwordx4 v[156:157], v[110:113], off
	v_exp_f32_e32 v63, v63
	v_mul_f32_e32 v204, v166, v166
	v_pk_add_f32 v[62:63], v[62:63], v[140:141]
	v_exp_f32_e32 v64, v64
	v_pk_mul_f32 v[14:15], v[14:15], v[196:197] op_sel_hi:[1,0]
	v_pk_mul_f32 v[16:17], v[16:17], v[196:197] op_sel_hi:[1,0]
	v_exp_f32_e32 v65, v65
; __device__ __forceinline__ unsigned pk2(float lo, float hi) { unsigned r; asm("v_cvt_pk_bf16_f32 %0, %1, %2" : "=v"(r) : "v"(lo), "v"(hi)); return r; }
; __device__ __forceinline__ float sigmoidf_(float v) { return __builtin_amdgcn_rcpf(1.0f + fexp(-v)); }
; #define PG8_BAR __builtin_amdgcn_s_barrier()
; template <class Epi, class Sched, bool ALIGN_EPI = true, bool SP2 = true>
; __device__ __forceinline__ void gemm_phase(LAS unsigned char* lds, const Gemm g, const Sched& S, const Epi& E) {
;     ...
;         if constexpr (ALIGN_EPI) { if (wr == 0) PG8_BAR; }
;         const bool keep = E(acc, cur, wr, wc, fr, fq);
;         if (!has_next) break;
;         if (!keep) {
; #pragma unroll
;         for (int a = 0; a < 2; ++a)
; #pragma unroll
;             for (int b = 0; b < 2; ++b)
; #pragma unroll
;                 for (int m = 0; m < 4; ++m)
; #pragma unroll
;                     for (int n = 0; n < 2; ++n) acc[a][b][m][n] = (f32x4){0.f, 0.f, 0.f, 0.f};
;         }
;         cur = nxt; cA = nA; cB = nB; ++ui;
;         if constexpr (ALIGN_EPI) { if (wr == 1) PG8_BAR; }
;     __device__ __forceinline__ bool operator()(f32x4 (&acc)[2][2][4][2], const pg8::Unit& u, int wr, int wc, int fr, int fq) const {
;     ...
;                 const int row = row0 + ai * 128 + m * 16; const float r = rr[ai * 4 + m];
;                 float o[8];
; #pragma unroll
;                 for (int n = 0; n < 2; ++n)
; #pragma unroll
;                     for (int j = 0; j < 4; ++j) { const float gv = acc[ai][0][m][n][j] * r, uv = acc[ai][1][m][n][j] * r; o[n * 4 + j] = gv * sigmoidf_(gv) * uv; }
;                 u32x4 w; w.x = pk2(o[0], o[1]); w.y = pk2(o[2], o[3]); w.z = pk2(o[4], o[5]); w.w = pk2(o[6], o[7]);
;                 *(u32x4*)(act + (size_t)row * FF + col0) = w;
;             }
;         return false;
	v_pk_mul_f32 v[6:7], v[6:7], v[196:197] op_sel_hi:[1,0]
	v_pk_add_f32 v[64:65], v[64:65], v[140:141]
	v_exp_f32_e32 v54, v54
	v_pk_mul_f32 v[8:9], v[8:9], v[196:197] op_sel_hi:[1,0]
	v_lshl_add_u64 v[156:157], v[156:157], 0, s[6:7]
	v_exp_f32_e32 v55, v55
	v_pk_mul_f32 v[74:75], v[74:75], v[204:205] op_sel_hi:[1,0]
	v_pk_add_f32 v[54:55], v[54:55], v[140:141]
	v_exp_f32_e32 v56, v56
	v_pk_mul_f32 v[76:77], v[76:77], v[204:205] op_sel_hi:[1,0]
	v_pk_mul_f32 v[66:67], v[66:67], v[204:205] op_sel_hi:[1,0]
	v_exp_f32_e32 v57, v57
	v_pk_mul_f32 v[68:69], v[68:69], v[204:205] op_sel_hi:[1,0]
	v_pk_add_f32 v[56:57], v[56:57], v[140:141]
	v_rcp_f32_e32 v94, v94
	v_mul_f32_e32 v206, v146, v146
	v_pk_mul_f32 v[58:59], v[58:59], v[206:207] op_sel_hi:[1,0]
	v_rcp_f32_e32 v95, v95
	v_pk_mul_f32 v[60:61], v[60:61], v[206:207] op_sel_hi:[1,0]
	v_pk_mul_f32 v[90:91], v[90:91], v[94:95]
	v_rcp_f32_e32 v96, v96
	v_cvt_pk_bf16_f32 v94, v90, v91
	v_pk_mul_f32 v[50:51], v[50:51], v[206:207] op_sel_hi:[1,0]
	v_rcp_f32_e32 v97, v97
	v_pk_mul_f32 v[52:53], v[52:53], v[206:207] op_sel_hi:[1,0]
	v_pk_mul_f32 v[92:93], v[92:93], v[96:97]
	v_rcp_f32_e32 v86, v86
	v_cvt_pk_bf16_f32 v95, v92, v93
	v_mul_f32_e32 v208, v148, v148
	v_rcp_f32_e32 v87, v87
	v_pk_mul_f32 v[42:43], v[42:43], v[208:209] op_sel_hi:[1,0]
	v_pk_mul_f32 v[82:83], v[82:83], v[86:87]
	v_rcp_f32_e32 v88, v88
	v_cvt_pk_bf16_f32 v96, v82, v83
	v_pk_mul_f32 v[44:45], v[44:45], v[208:209] op_sel_hi:[1,0]
	v_rcp_f32_e32 v89, v89
	v_pk_mul_f32 v[34:35], v[34:35], v[208:209] op_sel_hi:[1,0]
	v_pk_mul_f32 v[84:85], v[84:85], v[88:89]
	v_exp_f32_e32 v46, v46
	v_cvt_pk_bf16_f32 v97, v84, v85
	global_store_dwordx4 v[156:157], v[94:97], off
	v_exp_f32_e32 v47, v47
	v_lshl_add_u64 v[156:157], v[156:157], 0, s[6:7]
	v_pk_add_f32 v[46:47], v[46:47], v[140:141]
	v_exp_f32_e32 v48, v48
	s_mov_b32 s6, 0xdc000
	v_pk_mul_f32 v[36:37], v[36:37], v[208:209] op_sel_hi:[1,0]
	v_exp_f32_e32 v49, v49
	v_mul_f32_e32 v210, v144, v144
	v_pk_add_f32 v[48:49], v[48:49], v[140:141]
	v_exp_f32_e32 v38, v38
	v_pk_mul_f32 v[26:27], v[26:27], v[210:211] op_sel_hi:[1,0]
	v_pk_mul_f32 v[28:29], v[28:29], v[210:211] op_sel_hi:[1,0]
	v_exp_f32_e32 v39, v39
	v_pk_mul_f32 v[18:19], v[18:19], v[210:211] op_sel_hi:[1,0]
	v_pk_add_f32 v[38:39], v[38:39], v[140:141]
	v_exp_f32_e32 v40, v40
	v_pk_mul_f32 v[20:21], v[20:21], v[210:211] op_sel_hi:[1,0]
	v_mul_f32_e32 v212, v142, v142
	v_exp_f32_e32 v41, v41
	v_pk_mul_f32 v[10:11], v[10:11], v[212:213] op_sel_hi:[1,0]
	v_pk_add_f32 v[40:41], v[40:41], v[140:141]
	v_rcp_f32_e32 v78, v78
	v_pk_mul_f32 v[12:13], v[12:13], v[212:213] op_sel_hi:[1,0]
	v_pk_mul_f32 v[2:3], v[2:3], v[212:213] op_sel_hi:[1,0]
	v_rcp_f32_e32 v79, v79
	v_pk_mul_f32 v[4:5], v[4:5], v[212:213] op_sel_hi:[1,0]
	v_pk_mul_f32 v[74:75], v[74:75], v[78:79]
	v_rcp_f32_e32 v80, v80
	v_cvt_pk_bf16_f32 v78, v74, v75
	v_rcp_f32_e32 v81, v81
	v_rcp_f32_e32 v70, v70
	v_pk_mul_f32 v[76:77], v[76:77], v[80:81]
	v_rcp_f32_e32 v71, v71
	v_cvt_pk_bf16_f32 v79, v76, v77
	v_pk_mul_f32 v[66:67], v[66:67], v[70:71]
	v_rcp_f32_e32 v72, v72
	v_cvt_pk_bf16_f32 v80, v66, v67
	v_rcp_f32_e32 v73, v73
	v_exp_f32_e32 v30, v30
	v_pk_mul_f32 v[68:69], v[68:69], v[72:73]
	v_exp_f32_e32 v31, v31
	v_cvt_pk_bf16_f32 v81, v68, v69
	v_pk_add_f32 v[30:31], v[30:31], v[140:141]
	v_exp_f32_e32 v32, v32
	global_store_dwordx4 v[156:157], v[78:81], off
	v_lshl_add_u64 v[156:157], v[156:157], 0, s[6:7]
	v_exp_f32_e32 v33, v33
	s_mov_b32 s6, 0x2c000
	v_pk_add_f32 v[32:33], v[32:33], v[140:141]
	v_exp_f32_e32 v22, v22
	v_exp_f32_e32 v23, v23
	v_exp_f32_e32 v24, v24
	v_pk_add_f32 v[22:23], v[22:23], v[140:141]
	v_exp_f32_e32 v25, v25
	v_rcp_f32_e32 v62, v62
	v_pk_add_f32 v[24:25], v[24:25], v[140:141]
	v_rcp_f32_e32 v63, v63
	v_rcp_f32_e32 v64, v64
	v_pk_mul_f32 v[58:59], v[58:59], v[62:63]
	v_rcp_f32_e32 v65, v65
	v_cvt_pk_bf16_f32 v62, v58, v59
	v_pk_mul_f32 v[60:61], v[60:61], v[64:65]
	v_rcp_f32_e32 v54, v54
	v_cvt_pk_bf16_f32 v63, v60, v61
	v_rcp_f32_e32 v55, v55
	v_rcp_f32_e32 v56, v56
	v_pk_mul_f32 v[50:51], v[50:51], v[54:55]
	v_rcp_f32_e32 v57, v57
	v_cvt_pk_bf16_f32 v64, v50, v51
	v_pk_mul_f32 v[52:53], v[52:53], v[56:57]
	v_exp_f32_e32 v14, v14
	v_cvt_pk_bf16_f32 v65, v52, v53
	global_store_dwordx4 v[156:157], v[62:65], off
	v_exp_f32_e32 v15, v15
	v_lshl_add_u64 v[156:157], v[156:157], 0, s[6:7]
	v_pk_add_f32 v[14:15], v[14:15], v[140:141]
	v_exp_f32_e32 v16, v16
	v_exp_f32_e32 v17, v17
	v_exp_f32_e32 v6, v6
	v_pk_add_f32 v[16:17], v[16:17], v[140:141]
	v_exp_f32_e32 v7, v7
	v_exp_f32_e32 v8, v8
	v_pk_add_f32 v[6:7], v[6:7], v[140:141]
	v_exp_f32_e32 v9, v9
	v_rcp_f32_e32 v46, v46
	v_pk_add_f32 v[8:9], v[8:9], v[140:141]
	v_rcp_f32_e32 v47, v47
	v_rcp_f32_e32 v48, v48
	v_pk_mul_f32 v[42:43], v[42:43], v[46:47]
	v_rcp_f32_e32 v49, v49
	v_cvt_pk_bf16_f32 v46, v42, v43
	v_pk_mul_f32 v[44:45], v[44:45], v[48:49]
	v_rcp_f32_e32 v38, v38
	v_cvt_pk_bf16_f32 v47, v44, v45
	v_rcp_f32_e32 v39, v39
	v_rcp_f32_e32 v40, v40
	v_pk_mul_f32 v[34:35], v[34:35], v[38:39]
	v_rcp_f32_e32 v41, v41
	v_cvt_pk_bf16_f32 v48, v34, v35
	v_pk_mul_f32 v[36:37], v[36:37], v[40:41]
	v_rcp_f32_e32 v30, v30
	v_cvt_pk_bf16_f32 v49, v36, v37
	global_store_dwordx4 v[156:157], v[46:49], off
	v_rcp_f32_e32 v31, v31
	v_lshl_add_u64 v[156:157], v[156:157], 0, s[6:7]
	v_pk_mul_f32 v[26:27], v[26:27], v[30:31]
	v_rcp_f32_e32 v32, v32
	v_cvt_pk_bf16_f32 v30, v26, v27
	v_rcp_f32_e32 v33, v33
	v_rcp_f32_e32 v22, v22
	v_pk_mul_f32 v[28:29], v[28:29], v[32:33]
	v_rcp_f32_e32 v23, v23
	v_cvt_pk_bf16_f32 v31, v28, v29
	v_pk_mul_f32 v[18:19], v[18:19], v[22:23]
	v_rcp_f32_e32 v24, v24
	v_cvt_pk_bf16_f32 v32, v18, v19
	v_rcp_f32_e32 v25, v25
	v_rcp_f32_e32 v14, v14
	v_pk_mul_f32 v[20:21], v[20:21], v[24:25]
	v_rcp_f32_e32 v15, v15
	v_cvt_pk_bf16_f32 v33, v20, v21
	global_store_dwordx4 v[156:157], v[30:33], off
	v_rcp_f32_e32 v16, v16
	v_pk_mul_f32 v[10:11], v[10:11], v[14:15]
	v_lshl_add_u64 v[156:157], v[156:157], 0, s[6:7]
	v_rcp_f32_e32 v17, v17
	v_cvt_pk_bf16_f32 v14, v10, v11
	v_pk_mul_f32 v[12:13], v[12:13], v[16:17]
	v_rcp_f32_e32 v6, v6
	v_cvt_pk_bf16_f32 v15, v12, v13
	v_rcp_f32_e32 v7, v7
	v_rcp_f32_e32 v8, v8
	v_pk_mul_f32 v[2:3], v[2:3], v[6:7]
	v_rcp_f32_e32 v9, v9
	v_cvt_pk_bf16_f32 v16, v2, v3
	v_pk_mul_f32 v[4:5], v[4:5], v[8:9]
	s_nop 0
	v_cvt_pk_bf16_f32 v17, v4, v5
	global_store_dwordx4 v[156:157], v[14:17], off
	s_mov_b64 s[6:7], -1
	s_andn2_b64 vcc, exec, s[0:1]
	s_cbranch_vccnz .LBB0_90
	s_andn2_b64 vcc, exec, s[4:5]
	s_cbranch_vccnz .LBB0_89
	s_barrier
	s_branch .LBB0_89

; __device__ __forceinline__ unsigned pk2(float lo, float hi) { unsigned r; asm("v_cvt_pk_bf16_f32 %0, %1, %2" : "=v"(r) : "v"(lo), "v"(hi)); return r; }
; __device__ __forceinline__ float sigmoidf_(float v) { return __builtin_amdgcn_rcpf(1.0f + fexp(-v)); }
; __device__ __forceinline__ void row_rstd8(const ssq_t* ss, int row0, float (&r)[8]) {
;     ssq_t sv[8];
; #pragma unroll
;     for (int k = 0; k < 8; ++k) sv[k] = ss[row0 + (k >> 2) * 128 + (k & 3) * 16];
;     asm volatile("" ::: "memory");
; #pragma unroll
;     for (int k = 0; k < 8; ++k) r[k] = rsqrtf((float)sv[k] * (1.0f / SSQ_SCALE) * (1.0f / D) + EPS);
; }
;     __device__ __forceinline__ bool operator()(f32x4 (&acc)[2][2][4][2], const pg8::Unit& u, int wr, int wc, int fr, int fq) const {
;         const int row0 = u.pm * 256 + wr * 64 + fr, col0 = u.pn * 128 + wc * 32 + 8 * fq;
;         float rr[8]; row_rstd8(ss, row0, rr);
; #pragma unroll
;         for (int ai = 0; ai < 2; ++ai)
; #pragma unroll
;             for (int m = 0; m < 4; ++m) {
;                 const int row = row0 + ai * 128 + m * 16; const float r = rr[ai * 4 + m];
;                 float o[8];
; #pragma unroll
;                 for (int n = 0; n < 2; ++n)
; #pragma unroll
;                     for (int j = 0; j < 4; ++j) { const float gv = acc[ai][0][m][n][j] * r, uv = acc[ai][1][m][n][j] * r; o[n * 4 + j] = gv * sigmoidf_(gv) * uv; }
;                 u32x4 w; w.x = pk2(o[0], o[1]); w.y = pk2(o[2], o[3]); w.z = pk2(o[4], o[5]); w.w = pk2(o[6], o[7]);
;                 *(u32x4*)(act + (size_t)row * FF + col0) = w;
.LBB0_874:
	v_lshl_add_u32 v140, s57, 8, v151
	v_ashrrev_i32_e32 v141, 31, v140
	v_lshl_or_b32 v156, s56, 7, v155
	v_ashrrev_i32_e32 v157, 31, v156
	v_lshl_add_u64 v[142:143], v[140:141], 3, s[0:1]
	global_load_dwordx2 v[160:161], v[142:143], off
	global_load_dwordx2 v[162:163], v[142:143], off offset:128
	global_load_dwordx2 v[164:165], v[142:143], off offset:256
	global_load_dwordx2 v[166:167], v[142:143], off offset:384
	global_load_dwordx2 v[146:147], v[142:143], off offset:1024
	global_load_dwordx2 v[148:149], v[142:143], off offset:1152
	global_load_dwordx2 v[144:145], v[142:143], off offset:1280
	s_nop 0
	global_load_dwordx2 v[142:143], v[142:143], off offset:1408
	v_lshlrev_b64 v[156:157], 1, v[156:157]
	v_lshl_add_u64 v[156:157], v[156:157], 0, s[90:91]
	v_mad_i64_i32 v[156:157], s[4:5], v140, s37, v[156:157]
	v_mov_b32_e32 v140, 1.0
	v_mov_b32_e32 v141, 1.0
	v_pk_mul_f32 v[122:123], v[122:123], v[126:127]
	v_pk_mul_f32 v[124:125], v[124:125], v[128:129]
	v_pk_mul_f32 v[114:115], v[114:115], v[118:119]
	v_pk_mul_f32 v[116:117], v[116:117], v[120:121]
	v_pk_mul_f32 v[106:107], v[106:107], v[110:111]
	v_pk_mul_f32 v[108:109], v[108:109], v[112:113]
	v_pk_mul_f32 v[98:99], v[98:99], v[102:103]
	v_pk_mul_f32 v[100:101], v[100:101], v[104:105]
	v_pk_mul_f32 v[90:91], v[90:91], v[94:95]
	v_pk_mul_f32 v[92:93], v[92:93], v[96:97]
	v_pk_mul_f32 v[82:83], v[82:83], v[86:87]
	v_pk_mul_f32 v[84:85], v[84:85], v[88:89]
	v_pk_mul_f32 v[74:75], v[74:75], v[78:79]
	v_pk_mul_f32 v[76:77], v[76:77], v[80:81]
	v_pk_mul_f32 v[66:67], v[66:67], v[70:71]
	v_pk_mul_f32 v[68:69], v[68:69], v[72:73]
	v_pk_mul_f32 v[58:59], v[58:59], v[62:63]
	v_pk_mul_f32 v[60:61], v[60:61], v[64:65]
	v_pk_mul_f32 v[50:51], v[50:51], v[54:55]
	v_pk_mul_f32 v[52:53], v[52:53], v[56:57]
	v_pk_mul_f32 v[42:43], v[42:43], v[46:47]
	v_pk_mul_f32 v[44:45], v[44:45], v[48:49]
	v_pk_mul_f32 v[34:35], v[34:35], v[38:39]
	v_pk_mul_f32 v[36:37], v[36:37], v[40:41]
	v_pk_mul_f32 v[26:27], v[26:27], v[30:31]
	v_pk_mul_f32 v[28:29], v[28:29], v[32:33]
	v_pk_mul_f32 v[18:19], v[18:19], v[22:23]
	v_pk_mul_f32 v[20:21], v[20:21], v[24:25]
	v_pk_mul_f32 v[10:11], v[10:11], v[14:15]
	v_pk_mul_f32 v[12:13], v[12:13], v[16:17]
	v_pk_mul_f32 v[2:3], v[2:3], v[6:7]
	v_pk_mul_f32 v[4:5], v[4:5], v[8:9]
	s_mov_b32 s4, 0x2c000
	s_mov_b32 s5, 0
	s_waitcnt vmcnt(0)
	v_ffbh_u32_e32 v168, v161
	v_min_u32_e32 v168, 32, v168
	v_lshlrev_b64 v[160:161], v168, v[160:161]
	v_ffbh_u32_e32 v170, v163
	v_min_u32_e32 v198, 1, v160
	v_min_u32_e32 v170, 32, v170
	v_or_b32_e32 v198, v161, v198
	v_lshlrev_b64 v[162:163], v170, v[162:163]
	v_ffbh_u32_e32 v172, v165
	v_cvt_f32_u32_e32 v198, v198
	v_sub_u32_e32 v168, 32, v168
	v_min_u32_e32 v200, 1, v162
	v_min_u32_e32 v172, 32, v172
	v_ldexp_f32 v198, v198, v168
	v_or_b32_e32 v200, v163, v200
	v_lshlrev_b64 v[164:165], v172, v[164:165]
	v_ffbh_u32_e32 v174, v167
	v_mul_f32_e32 v198, 0x33800000, v198
	v_cvt_f32_u32_e32 v200, v200
	v_sub_u32_e32 v170, 32, v170
	v_min_u32_e32 v202, 1, v164
	v_min_u32_e32 v174, 32, v174
	v_fmamk_f32 v198, v198, 0x3a000000, v218
	v_rsq_f32_e32 v160, v198
	v_ldexp_f32 v200, v200, v170
	v_or_b32_e32 v202, v165, v202
	v_lshlrev_b64 v[166:167], v174, v[166:167]
	v_ffbh_u32_e32 v176, v147
	v_mul_f32_e32 v200, 0x33800000, v200
	v_cvt_f32_u32_e32 v202, v202
	v_sub_u32_e32 v172, 32, v172
	v_min_u32_e32 v204, 1, v166
	v_min_u32_e32 v176, 32, v176
	v_fmamk_f32 v200, v200, 0x3a000000, v218
	v_rsq_f32_e32 v162, v200
	v_ldexp_f32 v202, v202, v172
	v_or_b32_e32 v204, v167, v204
	v_lshlrev_b64 v[146:147], v176, v[146:147]
	v_ffbh_u32_e32 v178, v149
	v_mul_f32_e32 v202, 0x33800000, v202
	v_cvt_f32_u32_e32 v204, v204
	v_sub_u32_e32 v174, 32, v174
	v_min_u32_e32 v206, 1, v146
	v_min_u32_e32 v178, 32, v178
	v_fmamk_f32 v202, v202, 0x3a000000, v218
	v_rsq_f32_e32 v164, v202
	v_ldexp_f32 v204, v204, v174
	v_or_b32_e32 v206, v147, v206
	v_lshlrev_b64 v[148:149], v178, v[148:149]
	v_ffbh_u32_e32 v194, v145
	v_mul_f32_e32 v204, 0x33800000, v204
	v_cvt_f32_u32_e32 v206, v206
	v_sub_u32_e32 v176, 32, v176
	v_min_u32_e32 v208, 1, v148
	v_min_u32_e32 v194, 32, v194
	v_mul_f32_e32 v168, 0xbfb8aa3b, v160
	v_fmamk_f32 v204, v204, 0x3a000000, v218
	v_rsq_f32_e32 v166, v204
	v_ldexp_f32 v206, v206, v176
	v_or_b32_e32 v208, v149, v208
	v_lshlrev_b64 v[144:145], v194, v[144:145]
	v_ffbh_u32_e32 v196, v143
	v_pk_mul_f32 v[126:127], v[126:127], v[168:169] op_sel_hi:[1,0]
	v_pk_mul_f32 v[128:129], v[128:129], v[168:169] op_sel_hi:[1,0]
	v_exp_f32_e32 v126, v126
	v_pk_mul_f32 v[118:119], v[118:119], v[168:169] op_sel_hi:[1,0]
	v_pk_mul_f32 v[120:121], v[120:121], v[168:169] op_sel_hi:[1,0]
	v_exp_f32_e32 v127, v127
	v_mul_f32_e32 v206, 0x33800000, v206
	v_cvt_f32_u32_e32 v208, v208
	v_exp_f32_e32 v128, v128
	v_sub_u32_e32 v178, 32, v178
	v_min_u32_e32 v210, 1, v144
	v_exp_f32_e32 v129, v129
	v_min_u32_e32 v196, 32, v196
	v_mul_f32_e32 v170, 0xbfb8aa3b, v162
	v_exp_f32_e32 v118, v118
	v_fmamk_f32 v206, v206, 0x3a000000, v218
	v_ldexp_f32 v208, v208, v178
	v_exp_f32_e32 v119, v119
	v_or_b32_e32 v210, v145, v210
	v_lshlrev_b64 v[142:143], v196, v[142:143]
	v_exp_f32_e32 v120, v120
	v_pk_mul_f32 v[110:111], v[110:111], v[170:171] op_sel_hi:[1,0]
	v_pk_mul_f32 v[112:113], v[112:113], v[170:171] op_sel_hi:[1,0]
	v_exp_f32_e32 v121, v121
	v_pk_mul_f32 v[102:103], v[102:103], v[170:171] op_sel_hi:[1,0]
	v_pk_mul_f32 v[104:105], v[104:105], v[170:171] op_sel_hi:[1,0]
	v_rsq_f32_e32 v146, v206
	v_mul_f32_e32 v208, 0x33800000, v208
	v_cvt_f32_u32_e32 v210, v210
	v_exp_f32_e32 v110, v110
	v_sub_u32_e32 v194, 32, v194
	v_min_u32_e32 v212, 1, v142
	v_exp_f32_e32 v111, v111
; __device__ __forceinline__ unsigned pk2(float lo, float hi) { unsigned r; asm("v_cvt_pk_bf16_f32 %0, %1, %2" : "=v"(r) : "v"(lo), "v"(hi)); return r; }
; __device__ __forceinline__ float sigmoidf_(float v) { return __builtin_amdgcn_rcpf(1.0f + fexp(-v)); }
;     __device__ __forceinline__ bool operator()(f32x4 (&acc)[2][2][4][2], const pg8::Unit& u, int wr, int wc, int fr, int fq) const {
;     ...
;                 const int row = row0 + ai * 128 + m * 16; const float r = rr[ai * 4 + m];
;                 float o[8];
; #pragma unroll
;                 for (int n = 0; n < 2; ++n)
; #pragma unroll
;                     for (int j = 0; j < 4; ++j) { const float gv = acc[ai][0][m][n][j] * r, uv = acc[ai][1][m][n][j] * r; o[n * 4 + j] = gv * sigmoidf_(gv) * uv; }
;                 u32x4 w; w.x = pk2(o[0], o[1]); w.y = pk2(o[2], o[3]); w.z = pk2(o[4], o[5]); w.w = pk2(o[6], o[7]);
;                 *(u32x4*)(act + (size_t)row * FF + col0) = w;
	v_mul_f32_e32 v172, 0xbfb8aa3b, v164
	v_fmamk_f32 v208, v208, 0x3a000000, v218
	v_exp_f32_e32 v112, v112
	v_ldexp_f32 v210, v210, v194
	v_or_b32_e32 v212, v143, v212
	v_exp_f32_e32 v113, v113
	v_pk_mul_f32 v[94:95], v[94:95], v[172:173] op_sel_hi:[1,0]
	v_pk_mul_f32 v[96:97], v[96:97], v[172:173] op_sel_hi:[1,0]
	v_exp_f32_e32 v102, v102
	v_pk_mul_f32 v[86:87], v[86:87], v[172:173] op_sel_hi:[1,0]
	v_pk_mul_f32 v[88:89], v[88:89], v[172:173] op_sel_hi:[1,0]
	v_exp_f32_e32 v103, v103
	v_mul_f32_e32 v210, 0x33800000, v210
	v_cvt_f32_u32_e32 v212, v212
	v_exp_f32_e32 v104, v104
	v_sub_u32_e32 v196, 32, v196
	v_pk_add_f32 v[126:127], v[126:127], v[140:141]
	v_exp_f32_e32 v105, v105
	v_pk_add_f32 v[128:129], v[128:129], v[140:141]
	v_pk_add_f32 v[118:119], v[118:119], v[140:141]
	v_rsq_f32_e32 v148, v208
	v_pk_add_f32 v[120:121], v[120:121], v[140:141]
	v_mul_f32_e32 v174, 0xbfb8aa3b, v166
	v_exp_f32_e32 v94, v94
	v_fmamk_f32 v210, v210, 0x3a000000, v218
	v_ldexp_f32 v212, v212, v196
	v_exp_f32_e32 v95, v95
	v_pk_mul_f32 v[78:79], v[78:79], v[174:175] op_sel_hi:[1,0]
	v_pk_mul_f32 v[80:81], v[80:81], v[174:175] op_sel_hi:[1,0]
	v_exp_f32_e32 v96, v96
	v_pk_mul_f32 v[70:71], v[70:71], v[174:175] op_sel_hi:[1,0]
	v_pk_mul_f32 v[72:73], v[72:73], v[174:175] op_sel_hi:[1,0]
	v_exp_f32_e32 v97, v97
	v_mul_f32_e32 v212, 0x33800000, v212
	v_pk_add_f32 v[110:111], v[110:111], v[140:141]
	v_exp_f32_e32 v86, v86
	v_pk_add_f32 v[112:113], v[112:113], v[140:141]
	v_pk_add_f32 v[102:103], v[102:103], v[140:141]
	v_exp_f32_e32 v87, v87
	v_pk_add_f32 v[104:105], v[104:105], v[140:141]
	v_mul_f32_e32 v176, 0xbfb8aa3b, v146
	v_exp_f32_e32 v88, v88
	v_fmamk_f32 v212, v212, 0x3a000000, v218
	v_mul_f32_e32 v198, v160, v160
	v_exp_f32_e32 v89, v89
	v_pk_mul_f32 v[62:63], v[62:63], v[176:177] op_sel_hi:[1,0]
	v_pk_mul_f32 v[64:65], v[64:65], v[176:177] op_sel_hi:[1,0]
	v_rcp_f32_e32 v126, v126
	v_pk_mul_f32 v[54:55], v[54:55], v[176:177] op_sel_hi:[1,0]
	v_pk_mul_f32 v[56:57], v[56:57], v[176:177] op_sel_hi:[1,0]
	v_rcp_f32_e32 v127, v127
	v_pk_mul_f32 v[122:123], v[122:123], v[198:199] op_sel_hi:[1,0]
	v_pk_mul_f32 v[124:125], v[124:125], v[198:199] op_sel_hi:[1,0]
	v_rcp_f32_e32 v128, v128
	v_pk_mul_f32 v[114:115], v[114:115], v[198:199] op_sel_hi:[1,0]
	v_pk_mul_f32 v[116:117], v[116:117], v[198:199] op_sel_hi:[1,0]
	v_rcp_f32_e32 v129, v129
	v_pk_add_f32 v[94:95], v[94:95], v[140:141]
	v_pk_add_f32 v[96:97], v[96:97], v[140:141]
	v_rcp_f32_e32 v118, v118
	v_pk_add_f32 v[86:87], v[86:87], v[140:141]
	v_pk_add_f32 v[88:89], v[88:89], v[140:141]
	v_rcp_f32_e32 v119, v119
	v_mul_f32_e32 v178, 0xbfb8aa3b, v148
	v_pk_mul_f32 v[122:123], v[122:123], v[126:127]
	v_rcp_f32_e32 v120, v120
	v_pk_mul_f32 v[124:125], v[124:125], v[128:129]
	v_pk_mul_f32 v[114:115], v[114:115], v[118:119]
	v_rcp_f32_e32 v121, v121
	v_mul_f32_e32 v200, v162, v162
	v_pk_mul_f32 v[116:117], v[116:117], v[120:121]
	v_rsq_f32_e32 v144, v210
	v_pk_mul_f32 v[46:47], v[46:47], v[178:179] op_sel_hi:[1,0]
	v_pk_mul_f32 v[48:49], v[48:49], v[178:179] op_sel_hi:[1,0]
	v_exp_f32_e32 v78, v78
	v_pk_mul_f32 v[38:39], v[38:39], v[178:179] op_sel_hi:[1,0]
	v_pk_mul_f32 v[40:41], v[40:41], v[178:179] op_sel_hi:[1,0]
	v_exp_f32_e32 v79, v79
	v_cvt_pk_bf16_f32 v126, v122, v123
	v_cvt_pk_bf16_f32 v127, v124, v125
	v_exp_f32_e32 v80, v80
	v_cvt_pk_bf16_f32 v128, v114, v115
	v_cvt_pk_bf16_f32 v129, v116, v117
	v_exp_f32_e32 v81, v81
	v_pk_mul_f32 v[106:107], v[106:107], v[200:201] op_sel_hi:[1,0]
	v_pk_mul_f32 v[108:109], v[108:109], v[200:201] op_sel_hi:[1,0]
	v_exp_f32_e32 v70, v70
	v_pk_mul_f32 v[98:99], v[98:99], v[200:201] op_sel_hi:[1,0]
	v_pk_mul_f32 v[100:101], v[100:101], v[200:201] op_sel_hi:[1,0]
	v_exp_f32_e32 v71, v71
	v_pk_add_f32 v[78:79], v[78:79], v[140:141]
	v_pk_add_f32 v[80:81], v[80:81], v[140:141]
	v_exp_f32_e32 v72, v72
	v_pk_add_f32 v[70:71], v[70:71], v[140:141]
	v_mul_f32_e32 v194, 0xbfb8aa3b, v144
	v_exp_f32_e32 v73, v73
	global_store_dwordx4 v[156:157], v[126:129], off
	v_pk_add_f32 v[72:73], v[72:73], v[140:141]
	v_rcp_f32_e32 v110, v110
	v_mul_f32_e32 v202, v164, v164
	v_pk_mul_f32 v[30:31], v[30:31], v[194:195] op_sel_hi:[1,0]
	v_rcp_f32_e32 v111, v111
	v_pk_mul_f32 v[32:33], v[32:33], v[194:195] op_sel_hi:[1,0]
	v_pk_mul_f32 v[106:107], v[106:107], v[110:111]
	v_rcp_f32_e32 v112, v112
	v_pk_mul_f32 v[22:23], v[22:23], v[194:195] op_sel_hi:[1,0]
	v_pk_mul_f32 v[24:25], v[24:25], v[194:195] op_sel_hi:[1,0]
	v_rcp_f32_e32 v113, v113
	v_lshl_add_u64 v[156:157], v[156:157], 0, s[4:5]
	v_pk_mul_f32 v[108:109], v[108:109], v[112:113]
	v_rcp_f32_e32 v102, v102
	v_cvt_pk_bf16_f32 v110, v106, v107
	v_cvt_pk_bf16_f32 v111, v108, v109
	v_rcp_f32_e32 v103, v103
	v_pk_mul_f32 v[90:91], v[90:91], v[202:203] op_sel_hi:[1,0]
	v_pk_mul_f32 v[98:99], v[98:99], v[102:103]
	v_rcp_f32_e32 v104, v104
	v_cvt_pk_bf16_f32 v112, v98, v99
	v_pk_mul_f32 v[92:93], v[92:93], v[202:203] op_sel_hi:[1,0]
	v_rcp_f32_e32 v105, v105
	v_pk_mul_f32 v[82:83], v[82:83], v[202:203] op_sel_hi:[1,0]
	v_pk_mul_f32 v[100:101], v[100:101], v[104:105]
	v_rsq_f32_e32 v142, v212
	v_cvt_pk_bf16_f32 v113, v100, v101
	v_pk_mul_f32 v[84:85], v[84:85], v[202:203] op_sel_hi:[1,0]
	v_exp_f32_e32 v62, v62
	v_mul_f32_e32 v196, 0xbfb8aa3b, v142
	global_store_dwordx4 v[156:157], v[110:113], off
	v_exp_f32_e32 v63, v63
	v_mul_f32_e32 v204, v166, v166
	v_pk_add_f32 v[62:63], v[62:63], v[140:141]
	v_exp_f32_e32 v64, v64
	v_pk_mul_f32 v[14:15], v[14:15], v[196:197] op_sel_hi:[1,0]
	v_pk_mul_f32 v[16:17], v[16:17], v[196:197] op_sel_hi:[1,0]
	v_exp_f32_e32 v65, v65
	v_pk_mul_f32 v[6:7], v[6:7], v[196:197] op_sel_hi:[1,0]
; __device__ __forceinline__ unsigned pk2(float lo, float hi) { unsigned r; asm("v_cvt_pk_bf16_f32 %0, %1, %2" : "=v"(r) : "v"(lo), "v"(hi)); return r; }
; __device__ __forceinline__ float sigmoidf_(float v) { return __builtin_amdgcn_rcpf(1.0f + fexp(-v)); }
; #define PG8_BAR __builtin_amdgcn_s_barrier()
; template <class Epi, class Sched, bool ALIGN_EPI = true, bool SP2 = true>
; __device__ __forceinline__ void gemm_phase(LAS unsigned char* lds, const Gemm g, const Sched& S, const Epi& E) {
;     ...
;         if constexpr (ALIGN_EPI) { if (wr == 0) PG8_BAR; }
;         const bool keep = E(acc, cur, wr, wc, fr, fq);
;         if (!has_next) break;
;         if (!keep) {
; #pragma unroll
;         for (int a = 0; a < 2; ++a)
; #pragma unroll
;             for (int b = 0; b < 2; ++b)
; #pragma unroll
;                 for (int m = 0; m < 4; ++m)
; #pragma unroll
;                     for (int n = 0; n < 2; ++n) acc[a][b][m][n] = (f32x4){0.f, 0.f, 0.f, 0.f};
;         }
;         cur = nxt; cA = nA; cB = nB; ++ui;
;         if constexpr (ALIGN_EPI) { if (wr == 1) PG8_BAR; }
;     __device__ __forceinline__ bool operator()(f32x4 (&acc)[2][2][4][2], const pg8::Unit& u, int wr, int wc, int fr, int fq) const {
;     ...
;                 const int row = row0 + ai * 128 + m * 16; const float r = rr[ai * 4 + m];
;                 float o[8];
; #pragma unroll
;                 for (int n = 0; n < 2; ++n)
; #pragma unroll
;                     for (int j = 0; j < 4; ++j) { const float gv = acc[ai][0][m][n][j] * r, uv = acc[ai][1][m][n][j] * r; o[n * 4 + j] = gv * sigmoidf_(gv) * uv; }
;                 u32x4 w; w.x = pk2(o[0], o[1]); w.y = pk2(o[2], o[3]); w.z = pk2(o[4], o[5]); w.w = pk2(o[6], o[7]);
;                 *(u32x4*)(act + (size_t)row * FF + col0) = w;
;             }
;         return false;
	v_pk_add_f32 v[64:65], v[64:65], v[140:141]
	v_exp_f32_e32 v54, v54
	v_pk_mul_f32 v[8:9], v[8:9], v[196:197] op_sel_hi:[1,0]
	v_lshl_add_u64 v[156:157], v[156:157], 0, s[4:5]
	v_exp_f32_e32 v55, v55
	v_pk_mul_f32 v[74:75], v[74:75], v[204:205] op_sel_hi:[1,0]
	v_pk_add_f32 v[54:55], v[54:55], v[140:141]
	v_exp_f32_e32 v56, v56
	v_pk_mul_f32 v[76:77], v[76:77], v[204:205] op_sel_hi:[1,0]
	v_pk_mul_f32 v[66:67], v[66:67], v[204:205] op_sel_hi:[1,0]
	v_exp_f32_e32 v57, v57
	v_pk_mul_f32 v[68:69], v[68:69], v[204:205] op_sel_hi:[1,0]
	v_pk_add_f32 v[56:57], v[56:57], v[140:141]
	v_rcp_f32_e32 v94, v94
	v_mul_f32_e32 v206, v146, v146
	v_pk_mul_f32 v[58:59], v[58:59], v[206:207] op_sel_hi:[1,0]
	v_rcp_f32_e32 v95, v95
	v_pk_mul_f32 v[60:61], v[60:61], v[206:207] op_sel_hi:[1,0]
	v_pk_mul_f32 v[90:91], v[90:91], v[94:95]
	v_rcp_f32_e32 v96, v96
	v_cvt_pk_bf16_f32 v94, v90, v91
	v_pk_mul_f32 v[50:51], v[50:51], v[206:207] op_sel_hi:[1,0]
	v_rcp_f32_e32 v97, v97
	v_pk_mul_f32 v[52:53], v[52:53], v[206:207] op_sel_hi:[1,0]
	v_pk_mul_f32 v[92:93], v[92:93], v[96:97]
	v_rcp_f32_e32 v86, v86
	v_cvt_pk_bf16_f32 v95, v92, v93
	v_mul_f32_e32 v208, v148, v148
	v_rcp_f32_e32 v87, v87
	v_pk_mul_f32 v[42:43], v[42:43], v[208:209] op_sel_hi:[1,0]
	v_pk_mul_f32 v[82:83], v[82:83], v[86:87]
	v_rcp_f32_e32 v88, v88
	v_cvt_pk_bf16_f32 v96, v82, v83
	v_pk_mul_f32 v[44:45], v[44:45], v[208:209] op_sel_hi:[1,0]
	v_rcp_f32_e32 v89, v89
	v_pk_mul_f32 v[34:35], v[34:35], v[208:209] op_sel_hi:[1,0]
	v_pk_mul_f32 v[84:85], v[84:85], v[88:89]
	v_exp_f32_e32 v46, v46
	v_cvt_pk_bf16_f32 v97, v84, v85
	global_store_dwordx4 v[156:157], v[94:97], off
	v_exp_f32_e32 v47, v47
	v_lshl_add_u64 v[156:157], v[156:157], 0, s[4:5]
	v_pk_add_f32 v[46:47], v[46:47], v[140:141]
	v_exp_f32_e32 v48, v48
	s_mov_b32 s4, 0xdc000
	v_pk_mul_f32 v[36:37], v[36:37], v[208:209] op_sel_hi:[1,0]
	v_exp_f32_e32 v49, v49
	v_mul_f32_e32 v210, v144, v144
	v_pk_add_f32 v[48:49], v[48:49], v[140:141]
	v_exp_f32_e32 v38, v38
	v_pk_mul_f32 v[26:27], v[26:27], v[210:211] op_sel_hi:[1,0]
	v_pk_mul_f32 v[28:29], v[28:29], v[210:211] op_sel_hi:[1,0]
	v_exp_f32_e32 v39, v39
	v_pk_mul_f32 v[18:19], v[18:19], v[210:211] op_sel_hi:[1,0]
	v_pk_add_f32 v[38:39], v[38:39], v[140:141]
	v_exp_f32_e32 v40, v40
	v_pk_mul_f32 v[20:21], v[20:21], v[210:211] op_sel_hi:[1,0]
	v_mul_f32_e32 v212, v142, v142
	v_exp_f32_e32 v41, v41
	v_pk_mul_f32 v[10:11], v[10:11], v[212:213] op_sel_hi:[1,0]
	v_pk_add_f32 v[40:41], v[40:41], v[140:141]
	v_rcp_f32_e32 v78, v78
	v_pk_mul_f32 v[12:13], v[12:13], v[212:213] op_sel_hi:[1,0]
	v_pk_mul_f32 v[2:3], v[2:3], v[212:213] op_sel_hi:[1,0]
	v_rcp_f32_e32 v79, v79
	v_pk_mul_f32 v[4:5], v[4:5], v[212:213] op_sel_hi:[1,0]
	v_pk_mul_f32 v[74:75], v[74:75], v[78:79]
	v_rcp_f32_e32 v80, v80
	v_cvt_pk_bf16_f32 v78, v74, v75
	v_rcp_f32_e32 v81, v81
	v_rcp_f32_e32 v70, v70
	v_pk_mul_f32 v[76:77], v[76:77], v[80:81]
	v_rcp_f32_e32 v71, v71
	v_cvt_pk_bf16_f32 v79, v76, v77
	v_pk_mul_f32 v[66:67], v[66:67], v[70:71]
	v_rcp_f32_e32 v72, v72
	v_cvt_pk_bf16_f32 v80, v66, v67
	v_rcp_f32_e32 v73, v73
	v_exp_f32_e32 v30, v30
	v_pk_mul_f32 v[68:69], v[68:69], v[72:73]
	v_exp_f32_e32 v31, v31
	v_cvt_pk_bf16_f32 v81, v68, v69
	v_pk_add_f32 v[30:31], v[30:31], v[140:141]
	v_exp_f32_e32 v32, v32
	global_store_dwordx4 v[156:157], v[78:81], off
	v_lshl_add_u64 v[156:157], v[156:157], 0, s[4:5]
	v_exp_f32_e32 v33, v33
	s_mov_b32 s4, 0x2c000
	v_pk_add_f32 v[32:33], v[32:33], v[140:141]
	v_exp_f32_e32 v22, v22
	v_exp_f32_e32 v23, v23
	v_exp_f32_e32 v24, v24
	v_pk_add_f32 v[22:23], v[22:23], v[140:141]
	v_exp_f32_e32 v25, v25
	v_rcp_f32_e32 v62, v62
	v_pk_add_f32 v[24:25], v[24:25], v[140:141]
	v_rcp_f32_e32 v63, v63
	v_rcp_f32_e32 v64, v64
	v_pk_mul_f32 v[58:59], v[58:59], v[62:63]
	v_rcp_f32_e32 v65, v65
	v_cvt_pk_bf16_f32 v62, v58, v59
	v_pk_mul_f32 v[60:61], v[60:61], v[64:65]
	v_rcp_f32_e32 v54, v54
	v_cvt_pk_bf16_f32 v63, v60, v61
	v_rcp_f32_e32 v55, v55
	v_rcp_f32_e32 v56, v56
	v_pk_mul_f32 v[50:51], v[50:51], v[54:55]
	v_rcp_f32_e32 v57, v57
	v_cvt_pk_bf16_f32 v64, v50, v51
	v_pk_mul_f32 v[52:53], v[52:53], v[56:57]
	v_exp_f32_e32 v14, v14
	v_cvt_pk_bf16_f32 v65, v52, v53
	global_store_dwordx4 v[156:157], v[62:65], off
	v_exp_f32_e32 v15, v15
	v_lshl_add_u64 v[156:157], v[156:157], 0, s[4:5]
	v_pk_add_f32 v[14:15], v[14:15], v[140:141]
	v_exp_f32_e32 v16, v16
	v_exp_f32_e32 v17, v17
	v_exp_f32_e32 v6, v6
	v_pk_add_f32 v[16:17], v[16:17], v[140:141]
	v_exp_f32_e32 v7, v7
	v_exp_f32_e32 v8, v8
	v_pk_add_f32 v[6:7], v[6:7], v[140:141]
	v_exp_f32_e32 v9, v9
	v_rcp_f32_e32 v46, v46
	v_pk_add_f32 v[8:9], v[8:9], v[140:141]
	v_rcp_f32_e32 v47, v47
	v_rcp_f32_e32 v48, v48
	v_pk_mul_f32 v[42:43], v[42:43], v[46:47]
	v_rcp_f32_e32 v49, v49
	v_cvt_pk_bf16_f32 v46, v42, v43
	v_pk_mul_f32 v[44:45], v[44:45], v[48:49]
	v_rcp_f32_e32 v38, v38
	v_cvt_pk_bf16_f32 v47, v44, v45
	v_rcp_f32_e32 v39, v39
	v_rcp_f32_e32 v40, v40
	v_pk_mul_f32 v[34:35], v[34:35], v[38:39]
	v_rcp_f32_e32 v41, v41
	v_cvt_pk_bf16_f32 v48, v34, v35
	v_pk_mul_f32 v[36:37], v[36:37], v[40:41]
	v_rcp_f32_e32 v30, v30
	v_cvt_pk_bf16_f32 v49, v36, v37
	global_store_dwordx4 v[156:157], v[46:49], off
	v_rcp_f32_e32 v31, v31
	v_lshl_add_u64 v[156:157], v[156:157], 0, s[4:5]
	v_pk_mul_f32 v[26:27], v[26:27], v[30:31]
	v_rcp_f32_e32 v32, v32
	v_cvt_pk_bf16_f32 v30, v26, v27
	v_rcp_f32_e32 v33, v33
	v_rcp_f32_e32 v22, v22
	v_pk_mul_f32 v[28:29], v[28:29], v[32:33]
	v_rcp_f32_e32 v23, v23
	v_cvt_pk_bf16_f32 v31, v28, v29
	v_pk_mul_f32 v[18:19], v[18:19], v[22:23]
	v_rcp_f32_e32 v24, v24
	v_cvt_pk_bf16_f32 v32, v18, v19
	v_rcp_f32_e32 v25, v25
	v_rcp_f32_e32 v14, v14
	v_pk_mul_f32 v[20:21], v[20:21], v[24:25]
	v_rcp_f32_e32 v15, v15
	v_cvt_pk_bf16_f32 v33, v20, v21
	global_store_dwordx4 v[156:157], v[30:33], off
	v_rcp_f32_e32 v16, v16
	v_pk_mul_f32 v[10:11], v[10:11], v[14:15]
	v_lshl_add_u64 v[156:157], v[156:157], 0, s[4:5]
	v_rcp_f32_e32 v17, v17
	v_cvt_pk_bf16_f32 v14, v10, v11
	v_pk_mul_f32 v[12:13], v[12:13], v[16:17]
	v_rcp_f32_e32 v6, v6
	v_cvt_pk_bf16_f32 v15, v12, v13
	v_rcp_f32_e32 v7, v7
	v_rcp_f32_e32 v8, v8
	v_pk_mul_f32 v[2:3], v[2:3], v[6:7]
	v_rcp_f32_e32 v9, v9
	v_cvt_pk_bf16_f32 v16, v2, v3
	v_pk_mul_f32 v[4:5], v[4:5], v[8:9]
	s_nop 0
	v_cvt_pk_bf16_f32 v17, v4, v5
	global_store_dwordx4 v[156:157], v[14:17], off
	s_mov_b64 s[4:5], -1
	s_andn2_b64 vcc, exec, s[8:9]
	s_cbranch_vccnz .LBB0_867
	s_andn2_b64 vcc, exec, s[10:11]
	s_cbranch_vccnz .LBB0_866
	s_barrier
	s_branch .LBB0_866
